# first four QK K-fragment read pairs issued before the (saddr-form) LDS-DMA block so DMA issue overlaps LDS latency
# speedup vs baseline: 1.0050x; 1.0050x over previous
.LBB0_511:
	s_lshl_b32 s25, s76, 14
	v_add3_u32 v236, s25, v221, v220
	ds_read_b128 v[192:195], v236
	ds_read_b128 v[196:199], v236 offset:8192
	v_add3_u32 v236, s25, v222, v220
	ds_read_b128 v[200:203], v236
	ds_read_b128 v[204:207], v236 offset:8192
	v_add3_u32 v236, s25, v223, v220
	ds_read_b128 v[240:243], v236
	ds_read_b128 v[244:247], v236 offset:8192
	v_add3_u32 v236, s25, v224, v220
	ds_read_b128 v[248:251], v236
	ds_read_b128 v[252:255], v236 offset:8192
	s_cmp_gt_u32 s86, 61
	s_cbranch_scc1 .LBB0_513

.LBB0_513:
	s_waitcnt lgkmcnt(7)
	v_mfma_f32_32x32x16_bf16 v[144:159], v[192:195], v[160:163], 0
	s_waitcnt lgkmcnt(6)
	v_mfma_f32_32x32x16_bf16 v[128:143], v[196:199], v[160:163], 0
	v_add3_u32 v236, s25, v225, v220
	ds_read_b128 v[192:195], v236
	ds_read_b128 v[196:199], v236 offset:8192
	s_waitcnt lgkmcnt(7)
	v_mfma_f32_32x32x16_bf16 v[144:159], v[200:203], v[164:167], v[144:159]
	s_waitcnt lgkmcnt(6)
	v_mfma_f32_32x32x16_bf16 v[128:143], v[204:207], v[164:167], v[128:143]
	v_add3_u32 v236, s25, v227, v220
	ds_read_b128 v[200:203], v236
	ds_read_b128 v[204:207], v236 offset:8192
	s_waitcnt lgkmcnt(7)
	v_mfma_f32_32x32x16_bf16 v[144:159], v[240:243], v[168:171], v[144:159]
	s_waitcnt lgkmcnt(6)
	v_mfma_f32_32x32x16_bf16 v[128:143], v[244:247], v[168:171], v[128:143]
	v_add3_u32 v236, s25, v228, v220
	ds_read_b128 v[240:243], v236
	ds_read_b128 v[244:247], v236 offset:8192
	s_waitcnt lgkmcnt(7)
	v_mfma_f32_32x32x16_bf16 v[144:159], v[248:251], v[172:175], v[144:159]
	s_waitcnt lgkmcnt(6)
	v_mfma_f32_32x32x16_bf16 v[128:143], v[252:255], v[172:175], v[128:143]
	v_add3_u32 v236, s25, v229, v220
	ds_read_b128 v[248:251], v236
	ds_read_b128 v[252:255], v236 offset:8192
	s_waitcnt lgkmcnt(7)
	v_mfma_f32_32x32x16_bf16 v[144:159], v[192:195], v[176:179], v[144:159]
	s_waitcnt lgkmcnt(6)
	v_mfma_f32_32x32x16_bf16 v[128:143], v[196:199], v[176:179], v[128:143]
	s_waitcnt lgkmcnt(5)
	v_mfma_f32_32x32x16_bf16 v[144:159], v[200:203], v[180:183], v[144:159]
	s_waitcnt lgkmcnt(4)
	v_mfma_f32_32x32x16_bf16 v[128:143], v[204:207], v[180:183], v[128:143]
	s_waitcnt lgkmcnt(3)
	v_mfma_f32_32x32x16_bf16 v[144:159], v[240:243], v[184:187], v[144:159]
	s_waitcnt lgkmcnt(2)
	v_mfma_f32_32x32x16_bf16 v[128:143], v[244:247], v[184:187], v[128:143]
	s_waitcnt lgkmcnt(1)
	v_mfma_f32_32x32x16_bf16 v[144:159], v[248:251], v[188:191], v[144:159]
	s_waitcnt lgkmcnt(0)
	v_mfma_f32_32x32x16_bf16 v[128:143], v[252:255], v[188:191], v[128:143]
	s_nop 9
	v_max_f32_e32 v192, v144, v145
	v_max3_f32 v192, v192, v146, v147
	v_max3_f32 v192, v192, v148, v149
	v_max3_f32 v192, v192, v150, v151
	v_max3_f32 v192, v192, v152, v153
	v_max3_f32 v192, v192, v154, v155
	v_max3_f32 v192, v192, v156, v157
	v_max3_f32 v192, v192, v158, v159
	v_max3_f32 v192, v192, v128, v129
	v_max3_f32 v192, v192, v130, v131
	v_max3_f32 v192, v192, v132, v133
	v_max3_f32 v192, v192, v134, v135
	v_max3_f32 v192, v192, v136, v137
	v_max3_f32 v192, v192, v138, v139
	v_max3_f32 v192, v192, v140, v141
	v_max3_f32 v192, v192, v142, v143
	v_mov_b32_e32 v193, v192
	s_nop 1
	v_permlane32_swap_b32_e32 v192, v193
	v_max_f32_e32 v192, v192, v193
	v_sub_f32_e32 v193, v192, v231
	v_cmp_ge_f32_e32 vcc, s38, v193
	s_cmp_eq_u64 vcc, exec
	s_cbranch_scc1 .LBB0_517
	v_max_f32_e32 v234, v231, v192
	v_sub_f32_e32 v192, v231, v234
	v_mul_f32_e32 v192, 0x3e0293ee, v192
	v_exp_f32_e32 v233, v192
	v_mov_b32_e32 v231, v234
	v_mul_f32_e32 v237, 0xbe0293ee, v234
	v_mul_f32_e32 v232, v232, v233
	s_and_saveexec_b64 s[24:25], s[0:1]
	ds_write_b32 v226, v233 offset:128
	s_or_b64 exec, exec, s[24:25]
	s_waitcnt lgkmcnt(0)
	v_add_u32_e32 v192, s21, v210
	ds_read_b128 v[204:207], v192 offset:224
	ds_read_b128 v[200:203], v192 offset:192
	ds_read_b128 v[196:199], v192 offset:160
	ds_read_b128 v[192:195], v192 offset:128
	s_waitcnt lgkmcnt(3)
	v_pk_mul_f32 v[12:13], v[12:13], v[204:205]
	s_waitcnt lgkmcnt(2)
	v_pk_mul_f32 v[8:9], v[8:9], v[200:201]
	s_waitcnt lgkmcnt(1)
	v_pk_mul_f32 v[4:5], v[4:5], v[196:197]
	v_pk_mul_f32 v[14:15], v[14:15], v[206:207]
	v_pk_mul_f32 v[10:11], v[10:11], v[202:203]
	v_pk_mul_f32 v[6:7], v[6:7], v[198:199]
	s_waitcnt lgkmcnt(0)
	v_pk_mul_f32 v[2:3], v[2:3], v[194:195]
	v_pk_mul_f32 v[0:1], v[0:1], v[192:193]
	v_pk_mul_f32 v[124:125], v[124:125], v[204:205]
	v_pk_mul_f32 v[120:121], v[120:121], v[200:201]
	v_pk_mul_f32 v[116:117], v[116:117], v[196:197]
	v_pk_mul_f32 v[126:127], v[126:127], v[206:207]
	v_pk_mul_f32 v[122:123], v[122:123], v[202:203]
	v_pk_mul_f32 v[118:119], v[118:119], v[198:199]
	v_pk_mul_f32 v[114:115], v[114:115], v[194:195]
	v_pk_mul_f32 v[112:113], v[112:113], v[192:193]
	v_pk_mul_f32 v[108:109], v[108:109], v[204:205]
	v_pk_mul_f32 v[104:105], v[104:105], v[200:201]
	v_pk_mul_f32 v[100:101], v[100:101], v[196:197]
	v_pk_mul_f32 v[110:111], v[110:111], v[206:207]
	v_pk_mul_f32 v[106:107], v[106:107], v[202:203]
	v_pk_mul_f32 v[102:103], v[102:103], v[198:199]
	v_pk_mul_f32 v[98:99], v[98:99], v[194:195]
	v_pk_mul_f32 v[96:97], v[96:97], v[192:193]
	v_pk_mul_f32 v[92:93], v[92:93], v[204:205]
	v_pk_mul_f32 v[88:89], v[88:89], v[200:201]
	v_pk_mul_f32 v[84:85], v[84:85], v[196:197]
	v_pk_mul_f32 v[94:95], v[94:95], v[206:207]
	v_pk_mul_f32 v[90:91], v[90:91], v[202:203]
	v_pk_mul_f32 v[86:87], v[86:87], v[198:199]
	v_pk_mul_f32 v[82:83], v[82:83], v[194:195]
	v_pk_mul_f32 v[80:81], v[80:81], v[192:193]
	v_pk_mul_f32 v[76:77], v[76:77], v[204:205]
	v_pk_mul_f32 v[72:73], v[72:73], v[200:201]
	v_pk_mul_f32 v[68:69], v[68:69], v[196:197]
	v_pk_mul_f32 v[78:79], v[78:79], v[206:207]
	v_pk_mul_f32 v[74:75], v[74:75], v[202:203]
	v_pk_mul_f32 v[70:71], v[70:71], v[198:199]
	v_pk_mul_f32 v[66:67], v[66:67], v[194:195]
	v_pk_mul_f32 v[64:65], v[64:65], v[192:193]
	v_pk_mul_f32 v[60:61], v[60:61], v[204:205]
	v_pk_mul_f32 v[56:57], v[56:57], v[200:201]
	v_pk_mul_f32 v[52:53], v[52:53], v[196:197]
	v_pk_mul_f32 v[62:63], v[62:63], v[206:207]
	v_pk_mul_f32 v[58:59], v[58:59], v[202:203]
	v_pk_mul_f32 v[54:55], v[54:55], v[198:199]
	v_pk_mul_f32 v[50:51], v[50:51], v[194:195]
	v_pk_mul_f32 v[48:49], v[48:49], v[192:193]
	v_pk_mul_f32 v[44:45], v[44:45], v[204:205]
	v_pk_mul_f32 v[40:41], v[40:41], v[200:201]
	v_pk_mul_f32 v[36:37], v[36:37], v[196:197]
	v_pk_mul_f32 v[46:47], v[46:47], v[206:207]
	v_pk_mul_f32 v[42:43], v[42:43], v[202:203]
	v_pk_mul_f32 v[38:39], v[38:39], v[198:199]
	v_pk_mul_f32 v[34:35], v[34:35], v[194:195]
	v_pk_mul_f32 v[32:33], v[32:33], v[192:193]
	v_pk_mul_f32 v[28:29], v[28:29], v[204:205]
	v_pk_mul_f32 v[24:25], v[24:25], v[200:201]
	v_pk_mul_f32 v[20:21], v[20:21], v[196:197]
	v_pk_mul_f32 v[30:31], v[30:31], v[206:207]
	v_pk_mul_f32 v[26:27], v[26:27], v[202:203]
	v_pk_mul_f32 v[22:23], v[22:23], v[198:199]
	v_pk_mul_f32 v[18:19], v[18:19], v[194:195]
	v_pk_mul_f32 v[16:17], v[16:17], v[192:193]

.LBB0_904:
	s_lshl_b32 s25, s80, 14
	v_add3_u32 v236, s25, v221, v220
	ds_read_b128 v[192:195], v236
	ds_read_b128 v[196:199], v236 offset:8192
	v_add3_u32 v236, s25, v222, v220
	ds_read_b128 v[200:203], v236
	ds_read_b128 v[204:207], v236 offset:8192
	v_add3_u32 v236, s25, v223, v220
	ds_read_b128 v[240:243], v236
	ds_read_b128 v[244:247], v236 offset:8192
	v_add3_u32 v236, s25, v225, v220
	ds_read_b128 v[248:251], v236
	ds_read_b128 v[252:255], v236 offset:8192
	s_cmp_gt_u32 s86, 61
	s_cbranch_scc1 .LBB0_906

.LBB0_906:
	s_waitcnt lgkmcnt(7)
	v_mfma_f32_32x32x16_bf16 v[144:159], v[192:195], v[160:163], 0
	s_waitcnt lgkmcnt(6)
	v_mfma_f32_32x32x16_bf16 v[128:143], v[196:199], v[160:163], 0
	v_add3_u32 v236, s25, v226, v220
	ds_read_b128 v[192:195], v236
	ds_read_b128 v[196:199], v236 offset:8192
	s_waitcnt lgkmcnt(7)
	v_mfma_f32_32x32x16_bf16 v[144:159], v[200:203], v[164:167], v[144:159]
	s_waitcnt lgkmcnt(6)
	v_mfma_f32_32x32x16_bf16 v[128:143], v[204:207], v[164:167], v[128:143]
	v_add3_u32 v236, s25, v227, v220
	ds_read_b128 v[200:203], v236
	ds_read_b128 v[204:207], v236 offset:8192
	s_waitcnt lgkmcnt(7)
	v_mfma_f32_32x32x16_bf16 v[144:159], v[240:243], v[168:171], v[144:159]
	s_waitcnt lgkmcnt(6)
	v_mfma_f32_32x32x16_bf16 v[128:143], v[244:247], v[168:171], v[128:143]
	v_add3_u32 v236, s25, v228, v220
	ds_read_b128 v[240:243], v236
	ds_read_b128 v[244:247], v236 offset:8192
	s_waitcnt lgkmcnt(7)
	v_mfma_f32_32x32x16_bf16 v[144:159], v[248:251], v[172:175], v[144:159]
	s_waitcnt lgkmcnt(6)
	v_mfma_f32_32x32x16_bf16 v[128:143], v[252:255], v[172:175], v[128:143]
	v_add3_u32 v236, s25, v229, v220
	ds_read_b128 v[248:251], v236
	ds_read_b128 v[252:255], v236 offset:8192
	s_waitcnt lgkmcnt(7)
	v_mfma_f32_32x32x16_bf16 v[144:159], v[192:195], v[176:179], v[144:159]
	s_waitcnt lgkmcnt(6)
	v_mfma_f32_32x32x16_bf16 v[128:143], v[196:199], v[176:179], v[128:143]
	s_waitcnt lgkmcnt(5)
	v_mfma_f32_32x32x16_bf16 v[144:159], v[200:203], v[180:183], v[144:159]
	s_waitcnt lgkmcnt(4)
	v_mfma_f32_32x32x16_bf16 v[128:143], v[204:207], v[180:183], v[128:143]
	s_waitcnt lgkmcnt(3)
	v_mfma_f32_32x32x16_bf16 v[144:159], v[240:243], v[184:187], v[144:159]
	s_waitcnt lgkmcnt(2)
	v_mfma_f32_32x32x16_bf16 v[128:143], v[244:247], v[184:187], v[128:143]
	s_waitcnt lgkmcnt(1)
	v_mfma_f32_32x32x16_bf16 v[144:159], v[248:251], v[188:191], v[144:159]
	s_waitcnt lgkmcnt(0)
	v_mfma_f32_32x32x16_bf16 v[128:143], v[252:255], v[188:191], v[128:143]
	v_max_f32_e32 v194, v231, v231
	s_nop 9
	v_max_f32_e32 v192, v144, v145
	v_max3_f32 v192, v192, v146, v147
	v_max3_f32 v192, v192, v148, v149
	v_max3_f32 v192, v192, v150, v151
	v_max3_f32 v192, v192, v152, v153
	v_max3_f32 v192, v192, v154, v155
	v_max3_f32 v192, v192, v156, v157
	v_max3_f32 v192, v192, v158, v159
	v_max3_f32 v192, v192, v128, v129
	v_max3_f32 v192, v192, v130, v131
	v_max3_f32 v192, v192, v132, v133
	v_max3_f32 v192, v192, v134, v135
	v_max3_f32 v192, v192, v136, v137
	v_max3_f32 v192, v192, v138, v139
	v_max3_f32 v192, v192, v140, v141
	v_max3_f32 v192, v192, v142, v143
	v_mov_b32_e32 v193, v192
	s_nop 1
	v_permlane32_swap_b32_e32 v192, v193
	v_max_f32_e32 v192, v192, v193
	v_sub_f32_e32 v193, v192, v231
	v_cmp_ge_f32_e32 vcc, s42, v193
	s_cmp_eq_u64 vcc, exec
	s_cbranch_scc1 .LBB0_910
	v_max_f32_e32 v234, v194, v192
	v_sub_f32_e32 v192, v231, v234
	v_mul_f32_e32 v192, 0x3e0293ee, v192
	v_exp_f32_e32 v233, v192
	v_mov_b32_e32 v231, v234
	v_mul_f32_e32 v237, 0xbe0293ee, v234
	v_mul_f32_e32 v232, v232, v233
	s_and_saveexec_b64 s[24:25], s[0:1]
	ds_write_b32 v224, v233 offset:128
	s_or_b64 exec, exec, s[24:25]
	s_waitcnt lgkmcnt(0)
	v_add_u32_e32 v192, s21, v210
	ds_read_b128 v[204:207], v192 offset:224
	ds_read_b128 v[200:203], v192 offset:192
	ds_read_b128 v[196:199], v192 offset:160
	ds_read_b128 v[192:195], v192 offset:128
	s_waitcnt lgkmcnt(3)
	v_pk_mul_f32 v[12:13], v[12:13], v[204:205]
	s_waitcnt lgkmcnt(2)
	v_pk_mul_f32 v[8:9], v[8:9], v[200:201]
	s_waitcnt lgkmcnt(1)
	v_pk_mul_f32 v[4:5], v[4:5], v[196:197]
	v_pk_mul_f32 v[14:15], v[14:15], v[206:207]
	v_pk_mul_f32 v[10:11], v[10:11], v[202:203]
	v_pk_mul_f32 v[6:7], v[6:7], v[198:199]
	s_waitcnt lgkmcnt(0)
	v_pk_mul_f32 v[2:3], v[2:3], v[194:195]
	v_pk_mul_f32 v[0:1], v[0:1], v[192:193]
	v_pk_mul_f32 v[124:125], v[124:125], v[204:205]
	v_pk_mul_f32 v[120:121], v[120:121], v[200:201]
	v_pk_mul_f32 v[116:117], v[116:117], v[196:197]
	v_pk_mul_f32 v[126:127], v[126:127], v[206:207]
	v_pk_mul_f32 v[122:123], v[122:123], v[202:203]
	v_pk_mul_f32 v[118:119], v[118:119], v[198:199]
	v_pk_mul_f32 v[114:115], v[114:115], v[194:195]
	v_pk_mul_f32 v[112:113], v[112:113], v[192:193]
	v_pk_mul_f32 v[108:109], v[108:109], v[204:205]
	v_pk_mul_f32 v[104:105], v[104:105], v[200:201]
	v_pk_mul_f32 v[100:101], v[100:101], v[196:197]
	v_pk_mul_f32 v[110:111], v[110:111], v[206:207]
	v_pk_mul_f32 v[106:107], v[106:107], v[202:203]
	v_pk_mul_f32 v[102:103], v[102:103], v[198:199]
	v_pk_mul_f32 v[98:99], v[98:99], v[194:195]
	v_pk_mul_f32 v[96:97], v[96:97], v[192:193]
	v_pk_mul_f32 v[92:93], v[92:93], v[204:205]
	v_pk_mul_f32 v[88:89], v[88:89], v[200:201]
	v_pk_mul_f32 v[84:85], v[84:85], v[196:197]
	v_pk_mul_f32 v[94:95], v[94:95], v[206:207]
	v_pk_mul_f32 v[90:91], v[90:91], v[202:203]
	v_pk_mul_f32 v[86:87], v[86:87], v[198:199]
	v_pk_mul_f32 v[82:83], v[82:83], v[194:195]
	v_pk_mul_f32 v[80:81], v[80:81], v[192:193]
	v_pk_mul_f32 v[76:77], v[76:77], v[204:205]
	v_pk_mul_f32 v[72:73], v[72:73], v[200:201]
	v_pk_mul_f32 v[68:69], v[68:69], v[196:197]
	v_pk_mul_f32 v[78:79], v[78:79], v[206:207]
	v_pk_mul_f32 v[74:75], v[74:75], v[202:203]
	v_pk_mul_f32 v[70:71], v[70:71], v[198:199]
	v_pk_mul_f32 v[66:67], v[66:67], v[194:195]
	v_pk_mul_f32 v[64:65], v[64:65], v[192:193]
	v_pk_mul_f32 v[60:61], v[60:61], v[204:205]
	v_pk_mul_f32 v[56:57], v[56:57], v[200:201]
	v_pk_mul_f32 v[52:53], v[52:53], v[196:197]
	v_pk_mul_f32 v[62:63], v[62:63], v[206:207]
	v_pk_mul_f32 v[58:59], v[58:59], v[202:203]
	v_pk_mul_f32 v[54:55], v[54:55], v[198:199]
	v_pk_mul_f32 v[50:51], v[50:51], v[194:195]
	v_pk_mul_f32 v[48:49], v[48:49], v[192:193]
	v_pk_mul_f32 v[44:45], v[44:45], v[204:205]
	v_pk_mul_f32 v[40:41], v[40:41], v[200:201]
	v_pk_mul_f32 v[36:37], v[36:37], v[196:197]
	v_pk_mul_f32 v[46:47], v[46:47], v[206:207]
	v_pk_mul_f32 v[42:43], v[42:43], v[202:203]
	v_pk_mul_f32 v[38:39], v[38:39], v[198:199]
	v_pk_mul_f32 v[34:35], v[34:35], v[194:195]
	v_pk_mul_f32 v[32:33], v[32:33], v[192:193]
	v_pk_mul_f32 v[28:29], v[28:29], v[204:205]
	v_pk_mul_f32 v[24:25], v[24:25], v[200:201]
	v_pk_mul_f32 v[20:21], v[20:21], v[196:197]
	v_pk_mul_f32 v[30:31], v[30:31], v[206:207]
	v_pk_mul_f32 v[26:27], v[26:27], v[202:203]
	v_pk_mul_f32 v[22:23], v[22:23], v[198:199]
	v_pk_mul_f32 v[18:19], v[18:19], v[194:195]
	v_pk_mul_f32 v[16:17], v[16:17], v[192:193]
